# stack + prologue weight transposes: all 32 row loads of a tile issued before the first wait (was 4 rounds of 8)
# baseline (speedup 1.0000x reference)
.LBB0_14:
	v_lshl_add_u64 v[50:51], v[48:49], 0, s[2:3]
	v_lshl_add_u64 v[52:53], v[46:47], 0, s[2:3]
	v_lshl_add_u64 v[54:55], v[44:45], 0, s[2:3]
	v_lshl_add_u64 v[56:57], v[42:43], 0, s[2:3]
	v_lshl_add_u64 v[58:59], v[40:41], 0, s[2:3]
	v_lshl_add_u64 v[74:75], v[38:39], 0, s[2:3]
	v_lshl_add_u64 v[76:77], v[36:37], 0, s[2:3]
	v_lshl_add_u64 v[78:79], v[34:35], 0, s[2:3]
	global_load_dword v116, v[50:51], off nt
	s_nop 0
	global_load_dword v117, v[52:53], off nt
	s_nop 0
	global_load_dword v118, v[54:55], off nt
	s_nop 0
	global_load_dword v119, v[56:57], off nt
	s_nop 0
	global_load_dword v120, v[58:59], off nt
	s_nop 0
	global_load_dword v121, v[74:75], off nt
	s_nop 0
	global_load_dword v122, v[76:77], off nt
	s_nop 0
	global_load_dword v123, v[78:79], off nt
	s_nop 0
	s_add_u32 s2, s2, 0x10000
	s_addc_u32 s3, s3, 0
	v_lshl_add_u64 v[50:51], v[48:49], 0, s[2:3]
	v_lshl_add_u64 v[52:53], v[46:47], 0, s[2:3]
	v_lshl_add_u64 v[54:55], v[44:45], 0, s[2:3]
	v_lshl_add_u64 v[56:57], v[42:43], 0, s[2:3]
	v_lshl_add_u64 v[58:59], v[40:41], 0, s[2:3]
	v_lshl_add_u64 v[74:75], v[38:39], 0, s[2:3]
	v_lshl_add_u64 v[76:77], v[36:37], 0, s[2:3]
	v_lshl_add_u64 v[78:79], v[34:35], 0, s[2:3]
	global_load_dword v124, v[50:51], off nt
	s_nop 0
	global_load_dword v125, v[52:53], off nt
	s_nop 0
	global_load_dword v126, v[54:55], off nt
	s_nop 0
	global_load_dword v127, v[56:57], off nt
	s_nop 0
	global_load_dword v128, v[58:59], off nt
	s_nop 0
	global_load_dword v129, v[74:75], off nt
	s_nop 0
	global_load_dword v130, v[76:77], off nt
	s_nop 0
	global_load_dword v131, v[78:79], off nt
	s_nop 0
	s_add_u32 s2, s2, 0x10000
	s_addc_u32 s3, s3, 0
	v_lshl_add_u64 v[50:51], v[48:49], 0, s[2:3]
	v_lshl_add_u64 v[52:53], v[46:47], 0, s[2:3]
	v_lshl_add_u64 v[54:55], v[44:45], 0, s[2:3]
	v_lshl_add_u64 v[56:57], v[42:43], 0, s[2:3]
	v_lshl_add_u64 v[58:59], v[40:41], 0, s[2:3]
	v_lshl_add_u64 v[74:75], v[38:39], 0, s[2:3]
	v_lshl_add_u64 v[76:77], v[36:37], 0, s[2:3]
	v_lshl_add_u64 v[78:79], v[34:35], 0, s[2:3]
	global_load_dword v134, v[50:51], off nt
	s_nop 0
	global_load_dword v135, v[52:53], off nt
	s_nop 0
	global_load_dword v136, v[54:55], off nt
	s_nop 0
	global_load_dword v137, v[56:57], off nt
	s_nop 0
	global_load_dword v138, v[58:59], off nt
	s_nop 0
	global_load_dword v139, v[74:75], off nt
	s_nop 0
	global_load_dword v140, v[76:77], off nt
	s_nop 0
	global_load_dword v141, v[78:79], off nt
	s_nop 0
	s_add_u32 s2, s2, 0x10000
	s_addc_u32 s3, s3, 0
	v_lshl_add_u64 v[50:51], v[48:49], 0, s[2:3]
	v_lshl_add_u64 v[52:53], v[46:47], 0, s[2:3]
	v_lshl_add_u64 v[54:55], v[44:45], 0, s[2:3]
	v_lshl_add_u64 v[56:57], v[42:43], 0, s[2:3]
	v_lshl_add_u64 v[58:59], v[40:41], 0, s[2:3]
	v_lshl_add_u64 v[74:75], v[38:39], 0, s[2:3]
	v_lshl_add_u64 v[76:77], v[36:37], 0, s[2:3]
	v_lshl_add_u64 v[78:79], v[34:35], 0, s[2:3]
	global_load_dword v142, v[50:51], off nt
	s_nop 0
	global_load_dword v143, v[52:53], off nt
	s_nop 0
	global_load_dword v144, v[54:55], off nt
	s_nop 0
	global_load_dword v145, v[56:57], off nt
	s_nop 0
	global_load_dword v146, v[58:59], off nt
	s_nop 0
	global_load_dword v147, v[74:75], off nt
	s_nop 0
	global_load_dword v148, v[76:77], off nt
	s_nop 0
	global_load_dword v149, v[78:79], off nt
	s_nop 0
	s_add_u32 s2, s2, 0x10000
	s_addc_u32 s3, s3, 0
	v_add_u32_e32 v58, 0x400, v4
	s_waitcnt vmcnt(30)
	ds_write2_b32 v4, v116, v117 offset1:66
	s_waitcnt vmcnt(28)
	ds_write2_b32 v4, v118, v119 offset0:132 offset1:198
	s_waitcnt vmcnt(26)
	ds_write2_b32 v58, v120, v121 offset0:8 offset1:74
	s_waitcnt vmcnt(24)
	ds_write2_b32 v58, v122, v123 offset0:140 offset1:206
	v_add_u32_e32 v4, 0x840, v4
	v_add_u32_e32 v58, 0x400, v4
	s_waitcnt vmcnt(22)
	ds_write2_b32 v4, v124, v125 offset1:66
	s_waitcnt vmcnt(20)
	ds_write2_b32 v4, v126, v127 offset0:132 offset1:198
	s_waitcnt vmcnt(18)
	ds_write2_b32 v58, v128, v129 offset0:8 offset1:74
	s_waitcnt vmcnt(16)
	ds_write2_b32 v58, v130, v131 offset0:140 offset1:206
	v_add_u32_e32 v4, 0x840, v4
	v_add_u32_e32 v58, 0x400, v4
	s_waitcnt vmcnt(14)
	ds_write2_b32 v4, v134, v135 offset1:66
	s_waitcnt vmcnt(12)
	ds_write2_b32 v4, v136, v137 offset0:132 offset1:198
	s_waitcnt vmcnt(10)
	ds_write2_b32 v58, v138, v139 offset0:8 offset1:74
	s_waitcnt vmcnt(8)
	ds_write2_b32 v58, v140, v141 offset0:140 offset1:206
	v_add_u32_e32 v4, 0x840, v4
	v_add_u32_e32 v58, 0x400, v4
	s_waitcnt vmcnt(6)
	ds_write2_b32 v4, v142, v143 offset1:66
	s_waitcnt vmcnt(4)
	ds_write2_b32 v4, v144, v145 offset0:132 offset1:198
	s_waitcnt vmcnt(2)
	ds_write2_b32 v58, v146, v147 offset0:8 offset1:74
	s_waitcnt vmcnt(0)
	ds_write2_b32 v58, v148, v149 offset0:140 offset1:206
	v_add_u32_e32 v4, 0x840, v4
	s_add_i32 s2, s46, 0xffffe200
	s_cmpk_lt_u32 s2, 0x800
	s_cselect_b32 s3, s43, 0x2900000
	s_lshl_b32 s34, s46, 5
	s_and_b32 s34, s34, 0x3e0
	s_add_u32 s3, s20, s3
	s_addc_u32 s35, s21, 0
	s_waitcnt lgkmcnt(0)
	s_lshl_b32 s2, s2, 2
	s_and_b32 s2, s2, 0x1f80
	ds_read2_b32 v[38:39], v60 offset0:33 offset1:41
	ds_read2_b32 v[40:41], v60 offset1:8
	ds_read2_b32 v[42:43], v60 offset0:66 offset1:74
	ds_read2_b32 v[44:45], v60 offset0:99 offset1:107
	ds_read2_b32 v[46:47], v60 offset0:132 offset1:140
	ds_read2_b32 v[48:49], v60 offset0:165 offset1:173
	ds_read2_b32 v[50:51], v60 offset0:198 offset1:206
	ds_read2_b32 v[52:53], v60 offset0:231 offset1:239
	s_add_u32 s2, s3, s2
	s_addc_u32 s3, s35, 0
	v_lshlrev_b32_e32 v4, 1, v2
	v_lshl_add_u64 v[54:55], s[2:3], 0, v[4:5]
	v_or_b32_e32 v4, s34, v3
	v_lshlrev_b32_e32 v4, 13, v4
	s_waitcnt lgkmcnt(6)
	v_cvt_pk_bf16_f32 v34, v40, v38
	s_waitcnt lgkmcnt(4)
	v_cvt_pk_bf16_f32 v35, v42, v44
	s_waitcnt lgkmcnt(2)
	v_cvt_pk_bf16_f32 v36, v46, v48
	s_waitcnt lgkmcnt(0)
	v_cvt_pk_bf16_f32 v37, v50, v52
	v_lshl_add_u64 v[56:57], v[54:55], 0, v[4:5]
	global_store_dwordx4 v[56:57], v[34:37], off
	v_or_b32_e32 v4, s34, v61
	v_lshlrev_b32_e32 v4, 13, v4
	v_cvt_pk_bf16_f32 v34, v41, v39
	v_cvt_pk_bf16_f32 v35, v43, v45
	v_cvt_pk_bf16_f32 v36, v47, v49
	v_cvt_pk_bf16_f32 v37, v51, v53
	ds_read2_b32 v[40:41], v60 offset0:49 offset1:57
	ds_read2_b32 v[42:43], v60 offset0:16 offset1:24
	ds_read2_b32 v[44:45], v60 offset0:82 offset1:90
	ds_read2_b32 v[46:47], v60 offset0:115 offset1:123
	ds_read2_b32 v[48:49], v60 offset0:148 offset1:156
	ds_read2_b32 v[50:51], v60 offset0:181 offset1:189
	ds_read2_b32 v[52:53], v60 offset0:214 offset1:222
	ds_read2_b32 v[56:57], v60 offset0:247 offset1:255
	v_lshl_add_u64 v[38:39], v[54:55], 0, v[4:5]
	v_or_b32_e32 v4, s34, v62
	v_lshlrev_b32_e32 v4, 13, v4
	global_store_dwordx4 v[38:39], v[34:37], off
	v_lshl_add_u64 v[38:39], v[54:55], 0, v[4:5]
	v_or_b32_e32 v4, s34, v63
	s_waitcnt lgkmcnt(6)
	v_cvt_pk_bf16_f32 v34, v42, v40
	s_waitcnt lgkmcnt(4)
	v_cvt_pk_bf16_f32 v35, v44, v46
	s_waitcnt lgkmcnt(2)
	v_cvt_pk_bf16_f32 v36, v48, v50
	s_waitcnt lgkmcnt(0)
	v_cvt_pk_bf16_f32 v37, v52, v56
	v_lshlrev_b32_e32 v4, 13, v4
	global_store_dwordx4 v[38:39], v[34:37], off
	v_lshl_add_u64 v[38:39], v[54:55], 0, v[4:5]
	s_mov_b64 s[2:3], 0
	v_cvt_pk_bf16_f32 v34, v43, v41
	v_cvt_pk_bf16_f32 v35, v45, v47
	v_cvt_pk_bf16_f32 v36, v49, v51
	v_cvt_pk_bf16_f32 v37, v53, v57
	global_store_dwordx4 v[38:39], v[34:37], off
	s_waitcnt lgkmcnt(0)

.LBB0_25:
	v_lshl_add_u64 v[50:51], v[48:49], 0, s[2:3]
	v_lshl_add_u64 v[52:53], v[46:47], 0, s[2:3]
	v_lshl_add_u64 v[54:55], v[44:45], 0, s[2:3]
	v_lshl_add_u64 v[56:57], v[42:43], 0, s[2:3]
	v_lshl_add_u64 v[58:59], v[40:41], 0, s[2:3]
	v_lshl_add_u64 v[74:75], v[38:39], 0, s[2:3]
	v_lshl_add_u64 v[76:77], v[36:37], 0, s[2:3]
	v_lshl_add_u64 v[78:79], v[34:35], 0, s[2:3]
	global_load_dword v116, v[50:51], off nt
	s_nop 0
	global_load_dword v117, v[52:53], off nt
	s_nop 0
	global_load_dword v118, v[54:55], off nt
	s_nop 0
	global_load_dword v119, v[56:57], off nt
	s_nop 0
	global_load_dword v120, v[58:59], off nt
	s_nop 0
	global_load_dword v121, v[74:75], off nt
	s_nop 0
	global_load_dword v122, v[76:77], off nt
	s_nop 0
	global_load_dword v123, v[78:79], off nt
	s_nop 0
	s_add_u32 s2, s2, 0x10000
	s_addc_u32 s3, s3, 0
	v_lshl_add_u64 v[50:51], v[48:49], 0, s[2:3]
	v_lshl_add_u64 v[52:53], v[46:47], 0, s[2:3]
	v_lshl_add_u64 v[54:55], v[44:45], 0, s[2:3]
	v_lshl_add_u64 v[56:57], v[42:43], 0, s[2:3]
	v_lshl_add_u64 v[58:59], v[40:41], 0, s[2:3]
	v_lshl_add_u64 v[74:75], v[38:39], 0, s[2:3]
	v_lshl_add_u64 v[76:77], v[36:37], 0, s[2:3]
	v_lshl_add_u64 v[78:79], v[34:35], 0, s[2:3]
	global_load_dword v124, v[50:51], off nt
	s_nop 0
	global_load_dword v125, v[52:53], off nt
	s_nop 0
	global_load_dword v126, v[54:55], off nt
	s_nop 0
	global_load_dword v127, v[56:57], off nt
	s_nop 0
	global_load_dword v128, v[58:59], off nt
	s_nop 0
	global_load_dword v129, v[74:75], off nt
	s_nop 0
	global_load_dword v130, v[76:77], off nt
	s_nop 0
	global_load_dword v131, v[78:79], off nt
	s_nop 0
	s_add_u32 s2, s2, 0x10000
	s_addc_u32 s3, s3, 0
	v_lshl_add_u64 v[50:51], v[48:49], 0, s[2:3]
	v_lshl_add_u64 v[52:53], v[46:47], 0, s[2:3]
	v_lshl_add_u64 v[54:55], v[44:45], 0, s[2:3]
	v_lshl_add_u64 v[56:57], v[42:43], 0, s[2:3]
	v_lshl_add_u64 v[58:59], v[40:41], 0, s[2:3]
	v_lshl_add_u64 v[74:75], v[38:39], 0, s[2:3]
	v_lshl_add_u64 v[76:77], v[36:37], 0, s[2:3]
	v_lshl_add_u64 v[78:79], v[34:35], 0, s[2:3]
	global_load_dword v134, v[50:51], off nt
	s_nop 0
	global_load_dword v135, v[52:53], off nt
	s_nop 0
	global_load_dword v136, v[54:55], off nt
	s_nop 0
	global_load_dword v137, v[56:57], off nt
	s_nop 0
	global_load_dword v138, v[58:59], off nt
	s_nop 0
	global_load_dword v139, v[74:75], off nt
	s_nop 0
	global_load_dword v140, v[76:77], off nt
	s_nop 0
	global_load_dword v141, v[78:79], off nt
	s_nop 0
	s_add_u32 s2, s2, 0x10000
	s_addc_u32 s3, s3, 0
	v_lshl_add_u64 v[50:51], v[48:49], 0, s[2:3]
	v_lshl_add_u64 v[52:53], v[46:47], 0, s[2:3]
	v_lshl_add_u64 v[54:55], v[44:45], 0, s[2:3]
	v_lshl_add_u64 v[56:57], v[42:43], 0, s[2:3]
	v_lshl_add_u64 v[58:59], v[40:41], 0, s[2:3]
	v_lshl_add_u64 v[74:75], v[38:39], 0, s[2:3]
	v_lshl_add_u64 v[76:77], v[36:37], 0, s[2:3]
	v_lshl_add_u64 v[78:79], v[34:35], 0, s[2:3]
	global_load_dword v142, v[50:51], off nt
	s_nop 0
	global_load_dword v143, v[52:53], off nt
	s_nop 0
	global_load_dword v144, v[54:55], off nt
	s_nop 0
	global_load_dword v145, v[56:57], off nt
	s_nop 0
	global_load_dword v146, v[58:59], off nt
	s_nop 0
	global_load_dword v147, v[74:75], off nt
	s_nop 0
	global_load_dword v148, v[76:77], off nt
	s_nop 0
	global_load_dword v149, v[78:79], off nt
	s_nop 0
	s_add_u32 s2, s2, 0x10000
	s_addc_u32 s3, s3, 0
	v_add_u32_e32 v58, 0x400, v4
	s_waitcnt vmcnt(30)
	ds_write2_b32 v4, v116, v117 offset1:66
	s_waitcnt vmcnt(28)
	ds_write2_b32 v4, v118, v119 offset0:132 offset1:198
	s_waitcnt vmcnt(26)
	ds_write2_b32 v58, v120, v121 offset0:8 offset1:74
	s_waitcnt vmcnt(24)
	ds_write2_b32 v58, v122, v123 offset0:140 offset1:206
	v_add_u32_e32 v4, 0x840, v4
	v_add_u32_e32 v58, 0x400, v4
	s_waitcnt vmcnt(22)
	ds_write2_b32 v4, v124, v125 offset1:66
	s_waitcnt vmcnt(20)
	ds_write2_b32 v4, v126, v127 offset0:132 offset1:198
	s_waitcnt vmcnt(18)
	ds_write2_b32 v58, v128, v129 offset0:8 offset1:74
	s_waitcnt vmcnt(16)
	ds_write2_b32 v58, v130, v131 offset0:140 offset1:206
	v_add_u32_e32 v4, 0x840, v4
	v_add_u32_e32 v58, 0x400, v4
	s_waitcnt vmcnt(14)
	ds_write2_b32 v4, v134, v135 offset1:66
	s_waitcnt vmcnt(12)
	ds_write2_b32 v4, v136, v137 offset0:132 offset1:198
	s_waitcnt vmcnt(10)
	ds_write2_b32 v58, v138, v139 offset0:8 offset1:74
	s_waitcnt vmcnt(8)
	ds_write2_b32 v58, v140, v141 offset0:140 offset1:206
	v_add_u32_e32 v4, 0x840, v4
	v_add_u32_e32 v58, 0x400, v4
	s_waitcnt vmcnt(6)
	ds_write2_b32 v4, v142, v143 offset1:66
	s_waitcnt vmcnt(4)
	ds_write2_b32 v4, v144, v145 offset0:132 offset1:198
	s_waitcnt vmcnt(2)
	ds_write2_b32 v58, v146, v147 offset0:8 offset1:74
	s_waitcnt vmcnt(0)
	ds_write2_b32 v58, v148, v149 offset0:140 offset1:206
	v_add_u32_e32 v4, 0x840, v4
	s_lshl_b32 s2, s46, 1
	s_lshl_b32 s3, s46, 5
	s_waitcnt lgkmcnt(0)
	s_add_i32 s2, s2, 0x1e700
	s_and_b32 s34, s3, 0x3e0
	ds_read2_b32 v[38:39], v60 offset0:33 offset1:41
	ds_read2_b32 v[40:41], v60 offset1:8
	ds_read2_b32 v[42:43], v60 offset0:66 offset1:74
	ds_read2_b32 v[44:45], v60 offset0:99 offset1:107
	ds_read2_b32 v[46:47], v60 offset0:132 offset1:140
	ds_read2_b32 v[48:49], v60 offset0:165 offset1:173
	ds_read2_b32 v[50:51], v60 offset0:198 offset1:206
	ds_read2_b32 v[52:53], v60 offset0:231 offset1:239
	s_and_b32 s2, s2, 0x1ffc0
	v_or_b32_e32 v4, s34, v3
	s_lshl_b32 s2, s2, 1
	s_mov_b32 s3, s9
	v_mul_u32_u24_e32 v4, 0x300, v4
	v_lshl_add_u64 v[54:55], v[6:7], 0, s[2:3]
	v_lshlrev_b32_e32 v4, 1, v4
	v_lshl_add_u64 v[56:57], v[54:55], 0, v[4:5]
	v_or_b32_e32 v4, s34, v61
	s_waitcnt lgkmcnt(6)
	v_cvt_pk_bf16_f32 v34, v40, v38
	s_waitcnt lgkmcnt(4)
	v_cvt_pk_bf16_f32 v35, v42, v44
	s_waitcnt lgkmcnt(2)
	v_cvt_pk_bf16_f32 v36, v46, v48
	s_waitcnt lgkmcnt(0)
	v_cvt_pk_bf16_f32 v37, v50, v52
	v_mul_u32_u24_e32 v4, 0x300, v4
	global_store_dwordx4 v[56:57], v[34:37], off
	v_lshlrev_b32_e32 v4, 1, v4
	s_nop 0
	v_cvt_pk_bf16_f32 v34, v41, v39
	v_cvt_pk_bf16_f32 v35, v43, v45
	v_cvt_pk_bf16_f32 v36, v47, v49
	v_cvt_pk_bf16_f32 v37, v51, v53
	v_lshl_add_u64 v[38:39], v[54:55], 0, v[4:5]
	ds_read2_b32 v[40:41], v60 offset0:16 offset1:24
	ds_read2_b32 v[42:43], v60 offset0:49 offset1:57
	ds_read2_b32 v[44:45], v60 offset0:82 offset1:90
	ds_read2_b32 v[46:47], v60 offset0:115 offset1:123
	ds_read2_b32 v[48:49], v60 offset0:148 offset1:156
	ds_read2_b32 v[50:51], v60 offset0:181 offset1:189
	ds_read2_b32 v[52:53], v60 offset0:214 offset1:222
	ds_read2_b32 v[56:57], v60 offset0:247 offset1:255
	v_or_b32_e32 v4, s34, v62
	v_mul_u32_u24_e32 v4, 0x300, v4
	v_lshlrev_b32_e32 v4, 1, v4
	global_store_dwordx4 v[38:39], v[34:37], off
	v_lshl_add_u64 v[38:39], v[54:55], 0, v[4:5]
	v_or_b32_e32 v4, s34, v63
	v_mul_u32_u24_e32 v4, 0x300, v4
	s_waitcnt lgkmcnt(6)
	v_cvt_pk_bf16_f32 v34, v40, v42
	s_waitcnt lgkmcnt(4)
	v_cvt_pk_bf16_f32 v35, v44, v46
	s_waitcnt lgkmcnt(2)
	v_cvt_pk_bf16_f32 v36, v48, v50
	s_waitcnt lgkmcnt(0)
	v_cvt_pk_bf16_f32 v37, v52, v56
	v_lshlrev_b32_e32 v4, 1, v4
	global_store_dwordx4 v[38:39], v[34:37], off
	v_lshl_add_u64 v[38:39], v[54:55], 0, v[4:5]
	s_nop 0
	v_cvt_pk_bf16_f32 v34, v41, v43
	v_cvt_pk_bf16_f32 v35, v45, v47
	v_cvt_pk_bf16_f32 v36, v49, v51
	v_cvt_pk_bf16_f32 v37, v53, v57
	global_store_dwordx4 v[38:39], v[34:37], off
	s_waitcnt lgkmcnt(0)

.LBB0_39:
	v_lshl_add_u64 v[50:51], v[48:49], 0, s[2:3]
	v_lshl_add_u64 v[52:53], v[46:47], 0, s[2:3]
	v_lshl_add_u64 v[54:55], v[44:45], 0, s[2:3]
	v_lshl_add_u64 v[56:57], v[42:43], 0, s[2:3]
	v_lshl_add_u64 v[58:59], v[40:41], 0, s[2:3]
	v_lshl_add_u64 v[74:75], v[38:39], 0, s[2:3]
	v_lshl_add_u64 v[76:77], v[36:37], 0, s[2:3]
	v_lshl_add_u64 v[78:79], v[34:35], 0, s[2:3]
	global_load_dword v116, v[50:51], off nt
	s_nop 0
	global_load_dword v117, v[52:53], off nt
	s_nop 0
	global_load_dword v118, v[54:55], off nt
	s_nop 0
	global_load_dword v119, v[56:57], off nt
	s_nop 0
	global_load_dword v120, v[58:59], off nt
	s_nop 0
	global_load_dword v121, v[74:75], off nt
	s_nop 0
	global_load_dword v122, v[76:77], off nt
	s_nop 0
	global_load_dword v123, v[78:79], off nt
	s_nop 0
	s_add_u32 s2, s2, 0x10000
	s_addc_u32 s3, s3, 0
	v_lshl_add_u64 v[50:51], v[48:49], 0, s[2:3]
	v_lshl_add_u64 v[52:53], v[46:47], 0, s[2:3]
	v_lshl_add_u64 v[54:55], v[44:45], 0, s[2:3]
	v_lshl_add_u64 v[56:57], v[42:43], 0, s[2:3]
	v_lshl_add_u64 v[58:59], v[40:41], 0, s[2:3]
	v_lshl_add_u64 v[74:75], v[38:39], 0, s[2:3]
	v_lshl_add_u64 v[76:77], v[36:37], 0, s[2:3]
	v_lshl_add_u64 v[78:79], v[34:35], 0, s[2:3]
	global_load_dword v124, v[50:51], off nt
	s_nop 0
	global_load_dword v125, v[52:53], off nt
	s_nop 0
	global_load_dword v126, v[54:55], off nt
	s_nop 0
	global_load_dword v127, v[56:57], off nt
	s_nop 0
	global_load_dword v128, v[58:59], off nt
	s_nop 0
	global_load_dword v129, v[74:75], off nt
	s_nop 0
	global_load_dword v130, v[76:77], off nt
	s_nop 0
	global_load_dword v131, v[78:79], off nt
	s_nop 0
	s_add_u32 s2, s2, 0x10000
	s_addc_u32 s3, s3, 0
	v_lshl_add_u64 v[50:51], v[48:49], 0, s[2:3]
	v_lshl_add_u64 v[52:53], v[46:47], 0, s[2:3]
	v_lshl_add_u64 v[54:55], v[44:45], 0, s[2:3]
	v_lshl_add_u64 v[56:57], v[42:43], 0, s[2:3]
	v_lshl_add_u64 v[58:59], v[40:41], 0, s[2:3]
	v_lshl_add_u64 v[74:75], v[38:39], 0, s[2:3]
	v_lshl_add_u64 v[76:77], v[36:37], 0, s[2:3]
	v_lshl_add_u64 v[78:79], v[34:35], 0, s[2:3]
	global_load_dword v134, v[50:51], off nt
	s_nop 0
	global_load_dword v135, v[52:53], off nt
	s_nop 0
	global_load_dword v136, v[54:55], off nt
	s_nop 0
	global_load_dword v137, v[56:57], off nt
	s_nop 0
	global_load_dword v138, v[58:59], off nt
	s_nop 0
	global_load_dword v139, v[74:75], off nt
	s_nop 0
	global_load_dword v140, v[76:77], off nt
	s_nop 0
	global_load_dword v141, v[78:79], off nt
	s_nop 0
	s_add_u32 s2, s2, 0x10000
	s_addc_u32 s3, s3, 0
	v_lshl_add_u64 v[50:51], v[48:49], 0, s[2:3]
	v_lshl_add_u64 v[52:53], v[46:47], 0, s[2:3]
	v_lshl_add_u64 v[54:55], v[44:45], 0, s[2:3]
	v_lshl_add_u64 v[56:57], v[42:43], 0, s[2:3]
	v_lshl_add_u64 v[58:59], v[40:41], 0, s[2:3]
	v_lshl_add_u64 v[74:75], v[38:39], 0, s[2:3]
	v_lshl_add_u64 v[76:77], v[36:37], 0, s[2:3]
	v_lshl_add_u64 v[78:79], v[34:35], 0, s[2:3]
	global_load_dword v142, v[50:51], off nt
	s_nop 0
	global_load_dword v143, v[52:53], off nt
	s_nop 0
	global_load_dword v144, v[54:55], off nt
	s_nop 0
	global_load_dword v145, v[56:57], off nt
	s_nop 0
	global_load_dword v146, v[58:59], off nt
	s_nop 0
	global_load_dword v147, v[74:75], off nt
	s_nop 0
	global_load_dword v148, v[76:77], off nt
	s_nop 0
	global_load_dword v149, v[78:79], off nt
	s_nop 0
	s_add_u32 s2, s2, 0x10000
	s_addc_u32 s3, s3, 0
	v_add_u32_e32 v58, 0x400, v4
	s_waitcnt vmcnt(30)
	ds_write2_b32 v4, v116, v117 offset1:66
	s_waitcnt vmcnt(28)
	ds_write2_b32 v4, v118, v119 offset0:132 offset1:198
	s_waitcnt vmcnt(26)
	ds_write2_b32 v58, v120, v121 offset0:8 offset1:74
	s_waitcnt vmcnt(24)
	ds_write2_b32 v58, v122, v123 offset0:140 offset1:206
	v_add_u32_e32 v4, 0x840, v4
	v_add_u32_e32 v58, 0x400, v4
	s_waitcnt vmcnt(22)
	ds_write2_b32 v4, v124, v125 offset1:66
	s_waitcnt vmcnt(20)
	ds_write2_b32 v4, v126, v127 offset0:132 offset1:198
	s_waitcnt vmcnt(18)
	ds_write2_b32 v58, v128, v129 offset0:8 offset1:74
	s_waitcnt vmcnt(16)
	ds_write2_b32 v58, v130, v131 offset0:140 offset1:206
	v_add_u32_e32 v4, 0x840, v4
	v_add_u32_e32 v58, 0x400, v4
	s_waitcnt vmcnt(14)
	ds_write2_b32 v4, v134, v135 offset1:66
	s_waitcnt vmcnt(12)
	ds_write2_b32 v4, v136, v137 offset0:132 offset1:198
	s_waitcnt vmcnt(10)
	ds_write2_b32 v58, v138, v139 offset0:8 offset1:74
	s_waitcnt vmcnt(8)
	ds_write2_b32 v58, v140, v141 offset0:140 offset1:206
	v_add_u32_e32 v4, 0x840, v4
	v_add_u32_e32 v58, 0x400, v4
	s_waitcnt vmcnt(6)
	ds_write2_b32 v4, v142, v143 offset1:66
	s_waitcnt vmcnt(4)
	ds_write2_b32 v4, v144, v145 offset0:132 offset1:198
	s_waitcnt vmcnt(2)
	ds_write2_b32 v58, v146, v147 offset0:8 offset1:74
	s_waitcnt vmcnt(0)
	ds_write2_b32 v58, v148, v149 offset0:140 offset1:206
	v_add_u32_e32 v4, 0x840, v4
	s_waitcnt lgkmcnt(0)
	s_lshl_b32 s2, s46, 1
	ds_read2_b32 v[38:39], v60 offset0:33 offset1:41
	ds_read2_b32 v[40:41], v60 offset1:8
	ds_read2_b32 v[42:43], v60 offset0:66 offset1:74
	ds_read2_b32 v[44:45], v60 offset0:99 offset1:107
	ds_read2_b32 v[46:47], v60 offset0:132 offset1:140
	ds_read2_b32 v[48:49], v60 offset0:165 offset1:173
	ds_read2_b32 v[50:51], v60 offset0:198 offset1:206
	ds_read2_b32 v[52:53], v60 offset0:231 offset1:239
	s_add_i32 s2, s2, 0x1f400
	s_lshl_b32 s3, s46, 5
	s_and_b32 s2, s2, 0x1ffc0
	s_and_b32 s3, s3, 0x3e0
	s_lshl_b32 s8, s2, 1
	v_or_b32_e32 v4, s3, v3
	v_lshl_add_u64 v[54:55], v[12:13], 0, s[8:9]
	v_lshlrev_b32_e32 v4, 11, v4
	s_waitcnt lgkmcnt(6)
	v_cvt_pk_bf16_f32 v34, v40, v38
	s_waitcnt lgkmcnt(4)
	v_cvt_pk_bf16_f32 v35, v42, v44
	s_waitcnt lgkmcnt(2)
	v_cvt_pk_bf16_f32 v36, v46, v48
	s_waitcnt lgkmcnt(0)
	v_cvt_pk_bf16_f32 v37, v50, v52
	v_lshl_add_u64 v[56:57], v[54:55], 0, v[4:5]
	global_store_dwordx4 v[56:57], v[34:37], off
	v_or_b32_e32 v4, s3, v61
	v_lshlrev_b32_e32 v4, 11, v4
	v_cvt_pk_bf16_f32 v34, v41, v39
	v_cvt_pk_bf16_f32 v35, v43, v45
	v_cvt_pk_bf16_f32 v36, v47, v49
	v_cvt_pk_bf16_f32 v37, v51, v53
	ds_read2_b32 v[40:41], v60 offset0:49 offset1:57
	ds_read2_b32 v[42:43], v60 offset0:16 offset1:24
	ds_read2_b32 v[44:45], v60 offset0:82 offset1:90
	ds_read2_b32 v[46:47], v60 offset0:115 offset1:123
	ds_read2_b32 v[48:49], v60 offset0:148 offset1:156
	ds_read2_b32 v[50:51], v60 offset0:181 offset1:189
	ds_read2_b32 v[52:53], v60 offset0:214 offset1:222
	ds_read2_b32 v[56:57], v60 offset0:247 offset1:255
	v_lshl_add_u64 v[38:39], v[54:55], 0, v[4:5]
	v_or_b32_e32 v4, s3, v62
	v_lshlrev_b32_e32 v4, 11, v4
	global_store_dwordx4 v[38:39], v[34:37], off
	v_lshl_add_u64 v[38:39], v[54:55], 0, v[4:5]
	v_or_b32_e32 v4, s3, v63
	s_waitcnt lgkmcnt(6)
	v_cvt_pk_bf16_f32 v34, v42, v40
	s_waitcnt lgkmcnt(4)
	v_cvt_pk_bf16_f32 v35, v44, v46
	s_waitcnt lgkmcnt(2)
	v_cvt_pk_bf16_f32 v36, v48, v50
	s_waitcnt lgkmcnt(0)
	v_cvt_pk_bf16_f32 v37, v52, v56
	v_lshlrev_b32_e32 v4, 11, v4
	global_store_dwordx4 v[38:39], v[34:37], off
	v_lshl_add_u64 v[38:39], v[54:55], 0, v[4:5]
	s_nop 0
	v_cvt_pk_bf16_f32 v34, v43, v41
	v_cvt_pk_bf16_f32 v35, v45, v47
	v_cvt_pk_bf16_f32 v36, v49, v51
	v_cvt_pk_bf16_f32 v37, v53, v57
	global_store_dwordx4 v[38:39], v[34:37], off
	s_waitcnt lgkmcnt(0)
